# first k-iteration peeled (C=0, no accumulator zeroing) also for the FNet, P6 and P11 GEMMs
# baseline (speedup 1.0000x reference)
;     __device__ __forceinline__ bool next(int i, Unit& u) const { return decode(i * G + c, u); }
; #define PG8_STAGE(bufoff, gbase, voff) do { _Pragma("unroll") for (int _i = 0; _i < 2; ++_i) \
;         __builtin_amdgcn_global_load_lds((const unsigned*)((const char*)(gbase) + (voff)[_i]), (LAS unsigned*)(lds + (bufoff) + ldsw + _i * 8192), 16, 0, 0); } while (0)
; #define PG8_LDA(dst, b, h) do { _Pragma("unroll") for (int m = 0; m < 4; ++m) _Pragma("unroll") for (int k = 0; k < 2; ++k) dst[m][k] = *(const LAS bf16x8*)(lds + PG8_SA(b, h) + aoff + m * 2048 + k * 1024); } while (0)
; #define PG8_LDB(dst, b, h) do { _Pragma("unroll") for (int n = 0; n < 2; ++n) _Pragma("unroll") for (int k = 0; k < 2; ++k) dst[n][k] = *(const LAS bf16x8*)(lds + PG8_SB(b, h) + boff + n * 2048 + k * 1024); } while (0)
; #define PG8_WAIT_V(n) asm volatile("s_waitcnt vmcnt(" #n ")" ::: "memory")
; #define PG8_WAIT_L(n) asm volatile("s_waitcnt lgkmcnt(" #n ")" ::: "memory")
; #define PG8_BAR __builtin_amdgcn_s_barrier()
; #define PG8_SCHED __builtin_amdgcn_sched_barrier(0)
; template <class Epi, class Sched, bool DEFER>
; __device__ __forceinline__ void gemm_fast_core(LAS unsigned char* lds, const GemmP g, const Sched& S, const Epi& E, f32x4 (&acc)[2][2][4][2], Unit& cur) {
;     ...
;         const bool has_next = S.next(ui + 1, nxt);
;         const char* nA = has_next ? (const char*)g.aptr(nxt) : cA; const char* nB = has_next ? (const char*)g.bptr(nxt) : cB;
;         for (int t = 0; t < nt; t += 2) {
;             const bool last = (t == nt - 2);
;             const char* a1 = cA + (size_t)(t + 1) * kstep;
;             const char* a2 = last ? nA : cA + (size_t)(t + 2) * kstep; const char* b2 = last ? nB : cB + (size_t)(t + 2) * kstep;
;             const char* a3 = a2 + kstep; const char* b3 = b2 + kstep;
;             PG8_LDB(B0, 0, 0); PG8_LDB(B1, 0, 1); PG8_SCHED; PG8_LDA(At, 0, 0); PG8_STAGE(PG8_SA(1, 1), a1 + hstepA, voffA);
;             PG8_WAIT_V(8); PG8_WAIT_L(0); PG8_BAR; PG8_MMA(0, 0, At, B0); PG8_MMA(0, 1, At, B1); PG8_BAR; PG8_SCHED;
;             PG8_LDA(At, 0, 1); PG8_STAGE(PG8_SB(0, 0), b2, voffB); PG8_STAGE(PG8_SB(0, 1), b2 + hstepB, voffB); PG8_STAGE(PG8_SA(0, 0), a2, voffA);
;             PG8_WAIT_V(8); PG8_WAIT_L(0); PG8_BAR; PG8_MMA(1, 0, At, B0); PG8_MMA(1, 1, At, B1); PG8_BAR; PG8_SCHED;
.LBB0_1218:
	s_ashr_i32 s17, s16, 31
	s_lshl_b64 s[20:21], s[16:17], 21
	s_add_u32 s20, s48, s20
	s_addc_u32 s21, s49, s21
	s_and_b64 s[26:27], s[26:27], exec
	s_cselect_b32 s17, s21, s23
	s_cselect_b32 s41, s20, s22
	s_add_u32 s22, s22, 0x100080
	s_addc_u32 s23, s23, 0
	s_add_u32 s42, s24, 0x100
	s_addc_u32 s43, s25, 0
	s_mov_b32 s44, -2
	.p2align 6
	ds_read_b128 v[146:149], v142
	ds_read_b128 v[150:153], v142 offset:1024
	ds_read_b128 v[154:157], v142 offset:2048
	ds_read_b128 v[158:161], v142 offset:3072
	ds_read_b128 v[162:165], v143
	ds_read_b128 v[166:169], v143 offset:1024
	ds_read_b128 v[170:173], v143 offset:2048
	ds_read_b128 v[174:177], v143 offset:3072
	s_add_u32 s24, s22, 0xfff00080
	s_addc_u32 s25, s23, -1
	s_cmp_eq_u32 s44, 60
	s_cselect_b32 s27, s17, s25
	s_cselect_b32 s26, s41, s24
	s_cselect_b32 s25, s19, s43
	s_cselect_b32 s24, s18, s42
	v_lshl_add_u64 v[138:139], s[22:23], 0, v[134:135]
	s_add_i32 m0, s29, 0xc000
	ds_read_b128 v[178:181], v144
	ds_read_b128 v[182:185], v144 offset:1024
	ds_read_b128 v[192:195], v144 offset:2048
	ds_read_b128 v[196:199], v144 offset:3072
	ds_read_b128 v[200:203], v144 offset:4096
	ds_read_b128 v[204:207], v144 offset:5120
	ds_read_b128 v[208:211], v144 offset:6144
	ds_read_b128 v[212:215], v144 offset:7168
	global_load_lds_dwordx4 v[138:139], off
	v_lshl_add_u64 v[138:139], s[22:23], 0, v[136:137]
	s_add_i32 m0, s29, 0xe000
	s_nop 0
	global_load_lds_dwordx4 v[138:139], off
	s_waitcnt vmcnt(8)
	s_waitcnt lgkmcnt(0)
	s_barrier
	s_setprio 1
	s_waitcnt lgkmcnt(0)
	v_mfma_f32_16x16x32_bf16 v[124:127], v[146:149], v[178:181], 0
	v_mfma_f32_16x16x32_bf16 v[120:123], v[154:157], v[178:181], 0
	v_mfma_f32_16x16x32_bf16 v[112:115], v[146:149], v[192:195], 0
	v_mfma_f32_16x16x32_bf16 v[104:107], v[154:157], v[192:195], 0
	v_mfma_f32_16x16x32_bf16 v[96:99], v[146:149], v[200:203], 0
	v_mfma_f32_16x16x32_bf16 v[88:91], v[154:157], v[200:203], 0
	v_mfma_f32_16x16x32_bf16 v[80:83], v[146:149], v[208:211], 0
	v_mfma_f32_16x16x32_bf16 v[72:75], v[154:157], v[208:211], 0
	v_mfma_f32_16x16x32_bf16 v[124:127], v[150:153], v[182:185], v[124:127]
	v_mfma_f32_16x16x32_bf16 v[120:123], v[158:161], v[182:185], v[120:123]
	v_mfma_f32_16x16x32_bf16 v[112:115], v[150:153], v[196:199], v[112:115]
	v_mfma_f32_16x16x32_bf16 v[104:107], v[158:161], v[196:199], v[104:107]
	v_mfma_f32_16x16x32_bf16 v[96:99], v[150:153], v[204:207], v[96:99]
	v_mfma_f32_16x16x32_bf16 v[88:91], v[158:161], v[204:207], v[88:91]
	v_mfma_f32_16x16x32_bf16 v[80:83], v[150:153], v[212:215], v[80:83]
	v_mfma_f32_16x16x32_bf16 v[72:75], v[158:161], v[212:215], v[72:75]
	s_setprio 0
	s_setprio 1
	v_mfma_f32_16x16x32_bf16 v[116:119], v[162:165], v[178:181], 0
	v_mfma_f32_16x16x32_bf16 v[108:111], v[170:173], v[178:181], 0
	v_mfma_f32_16x16x32_bf16 v[100:103], v[162:165], v[192:195], 0
	v_mfma_f32_16x16x32_bf16 v[92:95], v[170:173], v[192:195], 0
	v_mfma_f32_16x16x32_bf16 v[84:87], v[162:165], v[200:203], 0
	v_mfma_f32_16x16x32_bf16 v[76:79], v[170:173], v[200:203], 0
	v_mfma_f32_16x16x32_bf16 v[68:71], v[162:165], v[208:211], 0
	v_mfma_f32_16x16x32_bf16 v[64:67], v[170:173], v[208:211], 0
	v_mfma_f32_16x16x32_bf16 v[116:119], v[166:169], v[182:185], v[116:119]
	v_mfma_f32_16x16x32_bf16 v[108:111], v[174:177], v[182:185], v[108:111]
	v_mfma_f32_16x16x32_bf16 v[100:103], v[166:169], v[196:199], v[100:103]
	v_mfma_f32_16x16x32_bf16 v[92:95], v[174:177], v[196:199], v[92:95]
	v_mfma_f32_16x16x32_bf16 v[84:87], v[166:169], v[204:207], v[84:87]
	v_mfma_f32_16x16x32_bf16 v[76:79], v[174:177], v[204:207], v[76:79]
	v_mfma_f32_16x16x32_bf16 v[68:71], v[166:169], v[212:215], v[68:71]
	v_mfma_f32_16x16x32_bf16 v[64:67], v[174:177], v[212:215], v[64:67]
	s_setprio 0
	s_barrier
	s_add_i32 s45, s36, s28
	v_lshl_add_u64 v[138:139], s[24:25], 0, v[128:129]
	s_mov_b32 m0, s45
	ds_read_b128 v[178:181], v144 offset:16384
	ds_read_b128 v[182:185], v144 offset:17408
	ds_read_b128 v[192:195], v144 offset:18432
	ds_read_b128 v[196:199], v144 offset:19456
	ds_read_b128 v[200:203], v144 offset:20480
	ds_read_b128 v[204:207], v144 offset:21504
	ds_read_b128 v[208:211], v144 offset:22528
	ds_read_b128 v[212:215], v144 offset:23552
	global_load_lds_dwordx4 v[138:139], off
	s_add_i32 m0, s45, 0x2000
	s_add_u32 s46, s24, 0x100000
	v_lshl_add_u64 v[186:187], s[24:25], 0, v[130:131]
	s_addc_u32 s47, s25, 0
	s_add_i32 s45, s37, s28
	global_load_lds_dwordx4 v[186:187], off
	v_lshl_add_u64 v[190:191], s[46:47], 0, v[128:129]
	s_mov_b32 m0, s45
	v_lshl_add_u64 v[216:217], s[26:27], 0, v[130:131]
	global_load_lds_dwordx4 v[190:191], off
	v_lshl_add_u64 v[190:191], s[46:47], 0, v[130:131]
	s_add_i32 m0, s45, 0x2000
	s_nop 0
	global_load_lds_dwordx4 v[190:191], off
	v_lshl_add_u64 v[190:191], s[26:27], 0, v[128:129]
	s_mov_b32 m0, s29
	s_nop 0
	global_load_lds_dwordx4 v[190:191], off
	s_mov_b32 m0, s30
	s_nop 0
	global_load_lds_dwordx4 v[216:217], off
	s_waitcnt vmcnt(8)
	s_waitcnt lgkmcnt(0)
	s_barrier
; #define PG8_STAGE(bufoff, gbase, voff) do { _Pragma("unroll") for (int _i = 0; _i < 2; ++_i) \
;         __builtin_amdgcn_global_load_lds((const unsigned*)((const char*)(gbase) + (voff)[_i]), (LAS unsigned*)(lds + (bufoff) + ldsw + _i * 8192), 16, 0, 0); } while (0)
; #define PG8_LDA(dst, b, h) do { _Pragma("unroll") for (int m = 0; m < 4; ++m) _Pragma("unroll") for (int k = 0; k < 2; ++k) dst[m][k] = *(const LAS bf16x8*)(lds + PG8_SA(b, h) + aoff + m * 2048 + k * 1024); } while (0)
; #define PG8_LDB(dst, b, h) do { _Pragma("unroll") for (int n = 0; n < 2; ++n) _Pragma("unroll") for (int k = 0; k < 2; ++k) dst[n][k] = *(const LAS bf16x8*)(lds + PG8_SB(b, h) + boff + n * 2048 + k * 1024); } while (0)
; #define PG8_MMA(ai, bj, At, Bt) do { __builtin_amdgcn_s_setprio(1); _Pragma("unroll") for (int m = 0; m < 4; ++m) _Pragma("unroll") for (int n = 0; n < 2; ++n) _Pragma("unroll") for (int k = 0; k < 2; ++k) \
;         acc[ai][bj][m][n] = __builtin_amdgcn_mfma_f32_16x16x32_bf16(Bt[n][k], At[m][k], acc[ai][bj][m][n], 0, 0, 0); __builtin_amdgcn_s_setprio(0); } while (0)
; #define PG8_WAIT_V(n) asm volatile("s_waitcnt vmcnt(" #n ")" ::: "memory")
; #define PG8_WAIT_L(n) asm volatile("s_waitcnt lgkmcnt(" #n ")" ::: "memory")
; #define PG8_BAR __builtin_amdgcn_s_barrier()
; #define PG8_SCHED __builtin_amdgcn_sched_barrier(0)
; template <class Epi, class Sched, bool DEFER>
; __device__ __forceinline__ void gemm_fast_core(LAS unsigned char* lds, const GemmP g, const Sched& S, const Epi& E, f32x4 (&acc)[2][2][4][2], Unit& cur) {
;     ...
;             PG8_WAIT_V(8); PG8_WAIT_L(0); PG8_BAR; PG8_MMA(1, 0, At, B0); PG8_MMA(1, 1, At, B1); PG8_BAR; PG8_SCHED;
;             PG8_LDB(B0, 1, 0); PG8_LDB(B1, 1, 1); PG8_SCHED; PG8_LDA(At, 1, 0); PG8_STAGE(PG8_SA(0, 1), a2 + hstepA, voffA);
;             PG8_WAIT_V(8); PG8_WAIT_L(0); PG8_BAR; PG8_MMA(0, 0, At, B0); PG8_MMA(0, 1, At, B1); PG8_BAR; PG8_SCHED;
;             PG8_LDA(At, 1, 1); PG8_STAGE(PG8_SB(1, 0), b3, voffB); PG8_STAGE(PG8_SB(1, 1), b3 + hstepB, voffB); PG8_STAGE(PG8_SA(1, 0), a3, voffA);
;             PG8_WAIT_V(8); PG8_WAIT_L(0); PG8_BAR; PG8_MMA(1, 0, At, B0); PG8_MMA(1, 1, At, B1); PG8_BAR; PG8_SCHED;
	s_setprio 1
	s_waitcnt lgkmcnt(0)
	v_mfma_f32_16x16x32_bf16 v[60:63], v[146:149], v[178:181], 0
	v_mfma_f32_16x16x32_bf16 v[56:59], v[154:157], v[178:181], 0
	v_mfma_f32_16x16x32_bf16 v[48:51], v[146:149], v[192:195], 0
	v_mfma_f32_16x16x32_bf16 v[40:43], v[154:157], v[192:195], 0
	v_mfma_f32_16x16x32_bf16 v[32:35], v[146:149], v[200:203], 0
	v_mfma_f32_16x16x32_bf16 v[24:27], v[154:157], v[200:203], 0
	v_mfma_f32_16x16x32_bf16 v[16:19], v[146:149], v[208:211], 0
	v_mfma_f32_16x16x32_bf16 v[8:11], v[154:157], v[208:211], 0
	v_mfma_f32_16x16x32_bf16 v[60:63], v[150:153], v[182:185], v[60:63]
	v_mfma_f32_16x16x32_bf16 v[56:59], v[158:161], v[182:185], v[56:59]
	v_mfma_f32_16x16x32_bf16 v[48:51], v[150:153], v[196:199], v[48:51]
	v_mfma_f32_16x16x32_bf16 v[40:43], v[158:161], v[196:199], v[40:43]
	v_mfma_f32_16x16x32_bf16 v[32:35], v[150:153], v[204:207], v[32:35]
	v_mfma_f32_16x16x32_bf16 v[24:27], v[158:161], v[204:207], v[24:27]
	v_mfma_f32_16x16x32_bf16 v[16:19], v[150:153], v[212:215], v[16:19]
	v_mfma_f32_16x16x32_bf16 v[8:11], v[158:161], v[212:215], v[8:11]
	s_setprio 0
	s_setprio 1
	v_mfma_f32_16x16x32_bf16 v[52:55], v[162:165], v[178:181], 0
	v_mfma_f32_16x16x32_bf16 v[44:47], v[170:173], v[178:181], 0
	v_mfma_f32_16x16x32_bf16 v[36:39], v[162:165], v[192:195], 0
	v_mfma_f32_16x16x32_bf16 v[28:31], v[170:173], v[192:195], 0
	v_mfma_f32_16x16x32_bf16 v[20:23], v[162:165], v[200:203], 0
	v_mfma_f32_16x16x32_bf16 v[12:15], v[170:173], v[200:203], 0
	v_mfma_f32_16x16x32_bf16 v[4:7], v[162:165], v[208:211], 0
	v_mfma_f32_16x16x32_bf16 v[0:3], v[170:173], v[208:211], 0
	v_mfma_f32_16x16x32_bf16 v[52:55], v[166:169], v[182:185], v[52:55]
	v_mfma_f32_16x16x32_bf16 v[44:47], v[174:177], v[182:185], v[44:47]
	v_mfma_f32_16x16x32_bf16 v[36:39], v[166:169], v[196:199], v[36:39]
	v_mfma_f32_16x16x32_bf16 v[28:31], v[174:177], v[196:199], v[28:31]
	v_mfma_f32_16x16x32_bf16 v[20:23], v[166:169], v[204:207], v[20:23]
	v_mfma_f32_16x16x32_bf16 v[12:15], v[174:177], v[204:207], v[12:15]
	v_mfma_f32_16x16x32_bf16 v[4:7], v[166:169], v[212:215], v[4:7]
	v_mfma_f32_16x16x32_bf16 v[0:3], v[174:177], v[212:215], v[0:3]
	s_setprio 0
	s_barrier
	s_add_i32 s45, 0, 0x18000
	v_add_u32_e32 v145, s45, v141
	s_add_i32 s46, 0, 0x1c000
	ds_read_b128 v[146:149], v145
	ds_read_b128 v[150:153], v145 offset:1024
	ds_read_b128 v[154:157], v145 offset:2048
	ds_read_b128 v[158:161], v145 offset:3072
	v_add_u32_e32 v145, s46, v141
	ds_read_b128 v[162:165], v145
	ds_read_b128 v[166:169], v145 offset:1024
	ds_read_b128 v[170:173], v145 offset:2048
	ds_read_b128 v[174:177], v145 offset:3072
	s_add_u32 s26, s26, 0x100000
	s_addc_u32 s27, s27, 0
	s_mov_b32 m0, s31
	v_lshl_add_u64 v[218:219], s[26:27], 0, v[128:129]
	ds_read_b128 v[178:181], v144 offset:32768
	ds_read_b128 v[182:185], v144 offset:33792
	ds_read_b128 v[192:195], v144 offset:34816
	ds_read_b128 v[196:199], v144 offset:35840
	ds_read_b128 v[200:203], v144 offset:36864
	ds_read_b128 v[204:207], v144 offset:37888
	ds_read_b128 v[208:211], v144 offset:38912
	ds_read_b128 v[212:215], v144 offset:39936
	global_load_lds_dwordx4 v[218:219], off
	v_lshl_add_u64 v[218:219], s[26:27], 0, v[130:131]
	s_mov_b32 m0, s33
	s_nop 0
	global_load_lds_dwordx4 v[218:219], off
	s_waitcnt vmcnt(8)
	s_waitcnt lgkmcnt(0)
	s_barrier
	s_setprio 1
	s_waitcnt lgkmcnt(0)
	v_mfma_f32_16x16x32_bf16 v[124:127], v[146:149], v[178:181], v[124:127]
	v_mfma_f32_16x16x32_bf16 v[120:123], v[154:157], v[178:181], v[120:123]
	v_mfma_f32_16x16x32_bf16 v[112:115], v[146:149], v[192:195], v[112:115]
	v_mfma_f32_16x16x32_bf16 v[104:107], v[154:157], v[192:195], v[104:107]
	v_mfma_f32_16x16x32_bf16 v[96:99], v[146:149], v[200:203], v[96:99]
	v_mfma_f32_16x16x32_bf16 v[88:91], v[154:157], v[200:203], v[88:91]
	v_mfma_f32_16x16x32_bf16 v[80:83], v[146:149], v[208:211], v[80:83]
	v_mfma_f32_16x16x32_bf16 v[72:75], v[154:157], v[208:211], v[72:75]
	v_mfma_f32_16x16x32_bf16 v[124:127], v[150:153], v[182:185], v[124:127]
	v_mfma_f32_16x16x32_bf16 v[120:123], v[158:161], v[182:185], v[120:123]
	v_mfma_f32_16x16x32_bf16 v[112:115], v[150:153], v[196:199], v[112:115]
	v_mfma_f32_16x16x32_bf16 v[104:107], v[158:161], v[196:199], v[104:107]
	v_mfma_f32_16x16x32_bf16 v[96:99], v[150:153], v[204:207], v[96:99]
	v_mfma_f32_16x16x32_bf16 v[88:91], v[158:161], v[204:207], v[88:91]
	v_mfma_f32_16x16x32_bf16 v[80:83], v[150:153], v[212:215], v[80:83]
	v_mfma_f32_16x16x32_bf16 v[72:75], v[158:161], v[212:215], v[72:75]
	s_setprio 0
	s_setprio 1
	v_mfma_f32_16x16x32_bf16 v[116:119], v[162:165], v[178:181], v[116:119]
	v_mfma_f32_16x16x32_bf16 v[108:111], v[170:173], v[178:181], v[108:111]
	v_mfma_f32_16x16x32_bf16 v[100:103], v[162:165], v[192:195], v[100:103]
	v_mfma_f32_16x16x32_bf16 v[92:95], v[170:173], v[192:195], v[92:95]
	v_mfma_f32_16x16x32_bf16 v[84:87], v[162:165], v[200:203], v[84:87]
	v_mfma_f32_16x16x32_bf16 v[76:79], v[170:173], v[200:203], v[76:79]
	v_mfma_f32_16x16x32_bf16 v[68:71], v[162:165], v[208:211], v[68:71]
	v_mfma_f32_16x16x32_bf16 v[64:67], v[170:173], v[208:211], v[64:67]
	v_mfma_f32_16x16x32_bf16 v[116:119], v[166:169], v[182:185], v[116:119]
	v_mfma_f32_16x16x32_bf16 v[108:111], v[174:177], v[182:185], v[108:111]
	v_mfma_f32_16x16x32_bf16 v[100:103], v[166:169], v[196:199], v[100:103]
	v_mfma_f32_16x16x32_bf16 v[92:95], v[174:177], v[196:199], v[92:95]
	v_mfma_f32_16x16x32_bf16 v[84:87], v[166:169], v[204:207], v[84:87]
	v_mfma_f32_16x16x32_bf16 v[76:79], v[174:177], v[204:207], v[76:79]
	v_mfma_f32_16x16x32_bf16 v[68:71], v[166:169], v[212:215], v[68:71]
	v_mfma_f32_16x16x32_bf16 v[64:67], v[174:177], v[212:215], v[64:67]
	s_setprio 0
	s_barrier
; #define PG8_STAGE(bufoff, gbase, voff) do { _Pragma("unroll") for (int _i = 0; _i < 2; ++_i) \
;         __builtin_amdgcn_global_load_lds((const unsigned*)((const char*)(gbase) + (voff)[_i]), (LAS unsigned*)(lds + (bufoff) + ldsw + _i * 8192), 16, 0, 0); } while (0)
; #define PG8_LDA(dst, b, h) do { _Pragma("unroll") for (int m = 0; m < 4; ++m) _Pragma("unroll") for (int k = 0; k < 2; ++k) dst[m][k] = *(const LAS bf16x8*)(lds + PG8_SA(b, h) + aoff + m * 2048 + k * 1024); } while (0)
; #define PG8_MMA(ai, bj, At, Bt) do { __builtin_amdgcn_s_setprio(1); _Pragma("unroll") for (int m = 0; m < 4; ++m) _Pragma("unroll") for (int n = 0; n < 2; ++n) _Pragma("unroll") for (int k = 0; k < 2; ++k) \
;         acc[ai][bj][m][n] = __builtin_amdgcn_mfma_f32_16x16x32_bf16(Bt[n][k], At[m][k], acc[ai][bj][m][n], 0, 0, 0); __builtin_amdgcn_s_setprio(0); } while (0)
; #define PG8_WAIT_V(n) asm volatile("s_waitcnt vmcnt(" #n ")" ::: "memory")
; #define PG8_WAIT_L(n) asm volatile("s_waitcnt lgkmcnt(" #n ")" ::: "memory")
; #define PG8_BAR __builtin_amdgcn_s_barrier()
; #define PG8_SCHED __builtin_amdgcn_sched_barrier(0)
; template <class Epi, class Sched, bool DEFER>
; __device__ __forceinline__ void gemm_fast_core(LAS unsigned char* lds, const GemmP g, const Sched& S, const Epi& E, f32x4 (&acc)[2][2][4][2], Unit& cur) {
;     ...
;         for (int t = 0; t < nt; t += 2) {
;     ...
;             PG8_LDA(At, 1, 1); PG8_STAGE(PG8_SB(1, 0), b3, voffB); PG8_STAGE(PG8_SB(1, 1), b3 + hstepB, voffB); PG8_STAGE(PG8_SA(1, 0), a3, voffA);
;             PG8_WAIT_V(8); PG8_WAIT_L(0); PG8_BAR; PG8_MMA(1, 0, At, B0); PG8_MMA(1, 1, At, B1); PG8_BAR; PG8_SCHED;
	s_add_i32 s26, s45, s28
	v_lshl_add_u64 v[138:139], v[138:139], 0, s[10:11]
	s_mov_b32 m0, s26
	ds_read_b128 v[178:181], v144 offset:49152
	ds_read_b128 v[182:185], v144 offset:50176
	ds_read_b128 v[192:195], v144 offset:51200
	ds_read_b128 v[196:199], v144 offset:52224
	ds_read_b128 v[200:203], v144 offset:53248
	ds_read_b128 v[204:207], v144 offset:54272
	ds_read_b128 v[208:211], v144 offset:55296
	ds_read_b128 v[212:215], v144 offset:56320
	global_load_lds_dwordx4 v[138:139], off
	s_add_i32 m0, s26, 0x2000
	s_add_u32 s24, s24, 0x100080
	v_lshl_add_u64 v[138:139], v[186:187], 0, s[10:11]
	s_addc_u32 s25, s25, 0
	s_add_i32 s26, s46, s28
	global_load_lds_dwordx4 v[138:139], off
	v_lshl_add_u64 v[138:139], s[24:25], 0, v[128:129]
	s_mov_b32 m0, s26
	s_nop 0
	global_load_lds_dwordx4 v[138:139], off
	v_lshl_add_u64 v[138:139], s[24:25], 0, v[130:131]
	s_add_i32 m0, s26, 0x2000
	s_nop 0
	global_load_lds_dwordx4 v[138:139], off
	v_lshl_add_u64 v[138:139], v[190:191], 0, s[10:11]
	s_mov_b32 m0, s34
	s_nop 0
	global_load_lds_dwordx4 v[138:139], off
	v_lshl_add_u64 v[138:139], v[216:217], 0, s[10:11]
	s_mov_b32 m0, s35
	s_nop 0
	global_load_lds_dwordx4 v[138:139], off
	s_waitcnt vmcnt(8)
	s_waitcnt lgkmcnt(0)
	s_barrier
	s_setprio 1
	s_waitcnt lgkmcnt(0)
	v_mfma_f32_16x16x32_bf16 v[60:63], v[146:149], v[178:181], v[60:63]
	v_mfma_f32_16x16x32_bf16 v[56:59], v[154:157], v[178:181], v[56:59]
	v_mfma_f32_16x16x32_bf16 v[48:51], v[146:149], v[192:195], v[48:51]
	v_mfma_f32_16x16x32_bf16 v[40:43], v[154:157], v[192:195], v[40:43]
	v_mfma_f32_16x16x32_bf16 v[32:35], v[146:149], v[200:203], v[32:35]
	v_mfma_f32_16x16x32_bf16 v[24:27], v[154:157], v[200:203], v[24:27]
	v_mfma_f32_16x16x32_bf16 v[16:19], v[146:149], v[208:211], v[16:19]
	v_mfma_f32_16x16x32_bf16 v[8:11], v[154:157], v[208:211], v[8:11]
	v_mfma_f32_16x16x32_bf16 v[60:63], v[150:153], v[182:185], v[60:63]
	v_mfma_f32_16x16x32_bf16 v[56:59], v[158:161], v[182:185], v[56:59]
	v_mfma_f32_16x16x32_bf16 v[48:51], v[150:153], v[196:199], v[48:51]
	v_mfma_f32_16x16x32_bf16 v[40:43], v[158:161], v[196:199], v[40:43]
	v_mfma_f32_16x16x32_bf16 v[32:35], v[150:153], v[204:207], v[32:35]
	v_mfma_f32_16x16x32_bf16 v[24:27], v[158:161], v[204:207], v[24:27]
	v_mfma_f32_16x16x32_bf16 v[16:19], v[150:153], v[212:215], v[16:19]
	v_mfma_f32_16x16x32_bf16 v[8:11], v[158:161], v[212:215], v[8:11]
	s_setprio 0
	s_setprio 1
	v_mfma_f32_16x16x32_bf16 v[52:55], v[162:165], v[178:181], v[52:55]
	v_mfma_f32_16x16x32_bf16 v[44:47], v[170:173], v[178:181], v[44:47]
	v_mfma_f32_16x16x32_bf16 v[36:39], v[162:165], v[192:195], v[36:39]
	v_mfma_f32_16x16x32_bf16 v[28:31], v[170:173], v[192:195], v[28:31]
	v_mfma_f32_16x16x32_bf16 v[20:23], v[162:165], v[200:203], v[20:23]
	v_mfma_f32_16x16x32_bf16 v[12:15], v[170:173], v[200:203], v[12:15]
	v_mfma_f32_16x16x32_bf16 v[4:7], v[162:165], v[208:211], v[4:7]
	v_mfma_f32_16x16x32_bf16 v[0:3], v[170:173], v[208:211], v[0:3]
	v_mfma_f32_16x16x32_bf16 v[52:55], v[166:169], v[182:185], v[52:55]
	v_mfma_f32_16x16x32_bf16 v[44:47], v[174:177], v[182:185], v[44:47]
	v_mfma_f32_16x16x32_bf16 v[36:39], v[166:169], v[196:199], v[36:39]
	v_mfma_f32_16x16x32_bf16 v[28:31], v[174:177], v[196:199], v[28:31]
	v_mfma_f32_16x16x32_bf16 v[20:23], v[166:169], v[204:207], v[20:23]
	v_mfma_f32_16x16x32_bf16 v[12:15], v[174:177], v[204:207], v[12:15]
	v_mfma_f32_16x16x32_bf16 v[4:7], v[166:169], v[212:215], v[4:7]
	v_mfma_f32_16x16x32_bf16 v[0:3], v[174:177], v[212:215], v[0:3]
	s_setprio 0
	s_barrier
	s_add_i32 s44, s44, 2
	s_add_u32 s22, s22, 0x100
	s_addc_u32 s23, s23, 0
	s_add_u32 s42, s42, 0x100
	s_addc_u32 s43, s43, 0
	s_cmp_gt_u32 s44, 61
	s_cbranch_scc0 .LBB0_1219
	s_branch .Lpeel_fn_done
	.p2align 6

; #define PG8_BAR __builtin_amdgcn_s_barrier()
; template <class Epi, class Sched, bool DEFER>
; __device__ __forceinline__ void gemm_fast_core(LAS unsigned char* lds, const GemmP g, const Sched& S, const Epi& E, f32x4 (&acc)[2][2][4][2], Unit& cur) {
;     ...
;         if (wr == 0) PG8_BAR;
.Lpeel_fn_done:
	s_and_b64 vcc, exec, s[12:13]
	s_cbranch_vccz .LBB0_1222
	s_barrier

;     __device__ __forceinline__ bool next(int i, Unit& u) const { return decode(i * G + c, u); }
; #define PG8_STAGE(bufoff, gbase, voff) do { _Pragma("unroll") for (int _i = 0; _i < 2; ++_i) \
;         __builtin_amdgcn_global_load_lds((const unsigned*)((const char*)(gbase) + (voff)[_i]), (LAS unsigned*)(lds + (bufoff) + ldsw + _i * 8192), 16, 0, 0); } while (0)
; #define PG8_LDA(dst, b, h) do { _Pragma("unroll") for (int m = 0; m < 4; ++m) _Pragma("unroll") for (int k = 0; k < 2; ++k) dst[m][k] = *(const LAS bf16x8*)(lds + PG8_SA(b, h) + aoff + m * 2048 + k * 1024); } while (0)
; #define PG8_LDB(dst, b, h) do { _Pragma("unroll") for (int n = 0; n < 2; ++n) _Pragma("unroll") for (int k = 0; k < 2; ++k) dst[n][k] = *(const LAS bf16x8*)(lds + PG8_SB(b, h) + boff + n * 2048 + k * 1024); } while (0)
; #define PG8_WAIT_V(n) asm volatile("s_waitcnt vmcnt(" #n ")" ::: "memory")
; #define PG8_WAIT_L(n) asm volatile("s_waitcnt lgkmcnt(" #n ")" ::: "memory")
; #define PG8_BAR __builtin_amdgcn_s_barrier()
; #define PG8_SCHED __builtin_amdgcn_sched_barrier(0)
; template <class Epi, class Sched, bool DEFER>
; __device__ __forceinline__ void gemm_fast_core(LAS unsigned char* lds, const GemmP g, const Sched& S, const Epi& E, f32x4 (&acc)[2][2][4][2], Unit& cur) {
;     ...
;         const bool has_next = S.next(ui + 1, nxt);
;         const char* nA = has_next ? (const char*)g.aptr(nxt) : cA; const char* nB = has_next ? (const char*)g.bptr(nxt) : cB;
;         for (int t = 0; t < nt; t += 2) {
;             const bool last = (t == nt - 2);
;             const char* a1 = cA + (size_t)(t + 1) * kstep;
;             const char* a2 = last ? nA : cA + (size_t)(t + 2) * kstep; const char* b2 = last ? nB : cB + (size_t)(t + 2) * kstep;
;             const char* a3 = a2 + kstep; const char* b3 = b2 + kstep;
;             PG8_LDB(B0, 0, 0); PG8_LDB(B1, 0, 1); PG8_SCHED; PG8_LDA(At, 0, 0); PG8_STAGE(PG8_SA(1, 1), a1 + hstepA, voffA);
;             PG8_WAIT_V(8); PG8_WAIT_L(0); PG8_BAR; PG8_MMA(0, 0, At, B0); PG8_MMA(0, 1, At, B1); PG8_BAR; PG8_SCHED;
;             PG8_LDA(At, 0, 1); PG8_STAGE(PG8_SB(0, 0), b2, voffB); PG8_STAGE(PG8_SB(0, 1), b2 + hstepB, voffB); PG8_STAGE(PG8_SA(0, 0), a2, voffA);
;             PG8_WAIT_V(8); PG8_WAIT_L(0); PG8_BAR; PG8_MMA(1, 0, At, B0); PG8_MMA(1, 1, At, B1); PG8_BAR; PG8_SCHED;
.LBB0_1409:
	s_xor_b64 s[28:29], s[20:21], -1
	s_ashr_i32 s13, s12, 31
	s_and_b64 vcc, exec, s[28:29]
	s_lshl_b64 s[22:23], s[12:13], 19
	s_add_u32 s22, s78, s22
	s_addc_u32 s23, s79, s23
	s_and_b64 s[24:25], s[20:21], exec
	s_cselect_b32 s5, s23, s31
	s_cselect_b32 s13, s22, s30
	s_ashr_i32 s11, s10, 31
	s_lshl_b64 s[24:25], s[10:11], 19
	s_add_u32 s24, s74, s24
	s_addc_u32 s25, s75, s25
	s_and_b64 s[36:37], s[20:21], exec
	s_cselect_b32 s11, s25, s35
	s_cselect_b32 s27, s24, s34
	s_add_u32 s30, s30, 0x40080
	s_addc_u32 s31, s31, 0
	s_add_u32 s33, s34, 0x100
	s_addc_u32 s47, s35, 0
	s_mov_b32 s48, -2
	s_waitcnt vmcnt(0)
	.p2align 6
	ds_read_b128 v[136:139], v151
	ds_read_b128 v[140:143], v151 offset:1024
	ds_read_b128 v[144:147], v151 offset:2048
	ds_read_b128 v[154:157], v151 offset:3072
	ds_read_b128 v[158:161], v152
	ds_read_b128 v[162:165], v152 offset:1024
	ds_read_b128 v[166:169], v152 offset:2048
	ds_read_b128 v[170:173], v152 offset:3072
	s_add_u32 s34, s30, 0xfffc0080
	s_addc_u32 s35, s31, -1
	s_cmp_eq_u32 s48, 12
	s_cselect_b32 s37, s5, s35
	s_cselect_b32 s36, s13, s34
	s_cselect_b32 s35, s11, s47
	s_cselect_b32 s34, s27, s33
	v_lshl_add_u64 v[186:187], s[30:31], 0, v[132:133]
	s_add_i32 m0, s39, 0xc000
	ds_read_b128 v[174:177], v153
	ds_read_b128 v[178:181], v153 offset:1024
	ds_read_b128 v[182:185], v153 offset:2048
	ds_read_b128 v[192:195], v153 offset:3072
	ds_read_b128 v[196:199], v153 offset:4096
	ds_read_b128 v[200:203], v153 offset:5120
	ds_read_b128 v[204:207], v153 offset:6144
	ds_read_b128 v[208:211], v153 offset:7168
	global_load_lds_dwordx4 v[186:187], off
	v_lshl_add_u64 v[186:187], s[30:31], 0, v[134:135]
	s_add_i32 m0, s39, 0xe000
	s_nop 0
	global_load_lds_dwordx4 v[186:187], off
	s_waitcnt vmcnt(8)
	s_waitcnt lgkmcnt(0)
	s_barrier
	s_setprio 1
	s_waitcnt lgkmcnt(0)
	v_mfma_f32_16x16x32_bf16 v[124:127], v[136:139], v[174:177], 0
	v_mfma_f32_16x16x32_bf16 v[120:123], v[144:147], v[174:177], 0
	v_mfma_f32_16x16x32_bf16 v[108:111], v[136:139], v[182:185], 0
	v_mfma_f32_16x16x32_bf16 v[104:107], v[144:147], v[182:185], 0
	v_mfma_f32_16x16x32_bf16 v[92:95], v[136:139], v[196:199], 0
	v_mfma_f32_16x16x32_bf16 v[88:91], v[144:147], v[196:199], 0
	v_mfma_f32_16x16x32_bf16 v[76:79], v[136:139], v[204:207], 0
	v_mfma_f32_16x16x32_bf16 v[72:75], v[144:147], v[204:207], 0
	v_mfma_f32_16x16x32_bf16 v[124:127], v[140:143], v[178:181], v[124:127]
	v_mfma_f32_16x16x32_bf16 v[120:123], v[154:157], v[178:181], v[120:123]
	v_mfma_f32_16x16x32_bf16 v[108:111], v[140:143], v[192:195], v[108:111]
	v_mfma_f32_16x16x32_bf16 v[104:107], v[154:157], v[192:195], v[104:107]
	v_mfma_f32_16x16x32_bf16 v[92:95], v[140:143], v[200:203], v[92:95]
	v_mfma_f32_16x16x32_bf16 v[88:91], v[154:157], v[200:203], v[88:91]
	v_mfma_f32_16x16x32_bf16 v[76:79], v[140:143], v[208:211], v[76:79]
	v_mfma_f32_16x16x32_bf16 v[72:75], v[154:157], v[208:211], v[72:75]
	s_setprio 0
	s_setprio 1
	v_mfma_f32_16x16x32_bf16 v[116:119], v[158:161], v[174:177], 0
	v_mfma_f32_16x16x32_bf16 v[112:115], v[166:169], v[174:177], 0
	v_mfma_f32_16x16x32_bf16 v[100:103], v[158:161], v[182:185], 0
	v_mfma_f32_16x16x32_bf16 v[96:99], v[166:169], v[182:185], 0
	v_mfma_f32_16x16x32_bf16 v[84:87], v[158:161], v[196:199], 0
	v_mfma_f32_16x16x32_bf16 v[80:83], v[166:169], v[196:199], 0
	v_mfma_f32_16x16x32_bf16 v[68:71], v[158:161], v[204:207], 0
	v_mfma_f32_16x16x32_bf16 v[64:67], v[166:169], v[204:207], 0
	v_mfma_f32_16x16x32_bf16 v[116:119], v[162:165], v[178:181], v[116:119]
	v_mfma_f32_16x16x32_bf16 v[112:115], v[170:173], v[178:181], v[112:115]
	v_mfma_f32_16x16x32_bf16 v[100:103], v[162:165], v[192:195], v[100:103]
	v_mfma_f32_16x16x32_bf16 v[96:99], v[170:173], v[192:195], v[96:99]
	v_mfma_f32_16x16x32_bf16 v[84:87], v[162:165], v[200:203], v[84:87]
	v_mfma_f32_16x16x32_bf16 v[80:83], v[170:173], v[200:203], v[80:83]
	v_mfma_f32_16x16x32_bf16 v[68:71], v[162:165], v[208:211], v[68:71]
	v_mfma_f32_16x16x32_bf16 v[64:67], v[170:173], v[208:211], v[64:67]
	s_setprio 0
	s_barrier
	s_add_i32 s49, s45, s38
	v_lshl_add_u64 v[186:187], s[34:35], 0, v[128:129]
	s_mov_b32 m0, s49
	ds_read_b128 v[174:177], v153 offset:16384
	ds_read_b128 v[178:181], v153 offset:17408
	ds_read_b128 v[182:185], v153 offset:18432
	ds_read_b128 v[192:195], v153 offset:19456
	ds_read_b128 v[196:199], v153 offset:20480
	ds_read_b128 v[200:203], v153 offset:21504
	ds_read_b128 v[204:207], v153 offset:22528
	ds_read_b128 v[208:211], v153 offset:23552
	global_load_lds_dwordx4 v[186:187], off
	s_add_i32 m0, s49, 0x2000
	s_add_u32 s50, s34, 0x40000
	v_lshl_add_u64 v[190:191], s[34:35], 0, v[130:131]
	s_addc_u32 s51, s35, 0
	s_add_i32 s49, s46, s38
	global_load_lds_dwordx4 v[190:191], off
	v_lshl_add_u64 v[212:213], s[50:51], 0, v[128:129]
	s_mov_b32 m0, s49
	v_lshl_add_u64 v[214:215], s[36:37], 0, v[130:131]
	global_load_lds_dwordx4 v[212:213], off
	v_lshl_add_u64 v[212:213], s[50:51], 0, v[130:131]
	s_add_i32 m0, s49, 0x2000
	s_nop 0
	global_load_lds_dwordx4 v[212:213], off
	v_lshl_add_u64 v[212:213], s[36:37], 0, v[128:129]
	s_mov_b32 m0, s39
	s_nop 0
	global_load_lds_dwordx4 v[212:213], off
	s_mov_b32 m0, s40
	s_nop 0
	global_load_lds_dwordx4 v[214:215], off
	s_waitcnt vmcnt(8)
	s_waitcnt lgkmcnt(0)
	s_barrier
; #define PG8_STAGE(bufoff, gbase, voff) do { _Pragma("unroll") for (int _i = 0; _i < 2; ++_i) \
;         __builtin_amdgcn_global_load_lds((const unsigned*)((const char*)(gbase) + (voff)[_i]), (LAS unsigned*)(lds + (bufoff) + ldsw + _i * 8192), 16, 0, 0); } while (0)
; #define PG8_LDA(dst, b, h) do { _Pragma("unroll") for (int m = 0; m < 4; ++m) _Pragma("unroll") for (int k = 0; k < 2; ++k) dst[m][k] = *(const LAS bf16x8*)(lds + PG8_SA(b, h) + aoff + m * 2048 + k * 1024); } while (0)
; #define PG8_LDB(dst, b, h) do { _Pragma("unroll") for (int n = 0; n < 2; ++n) _Pragma("unroll") for (int k = 0; k < 2; ++k) dst[n][k] = *(const LAS bf16x8*)(lds + PG8_SB(b, h) + boff + n * 2048 + k * 1024); } while (0)
; #define PG8_MMA(ai, bj, At, Bt) do { __builtin_amdgcn_s_setprio(1); _Pragma("unroll") for (int m = 0; m < 4; ++m) _Pragma("unroll") for (int n = 0; n < 2; ++n) _Pragma("unroll") for (int k = 0; k < 2; ++k) \
;         acc[ai][bj][m][n] = __builtin_amdgcn_mfma_f32_16x16x32_bf16(Bt[n][k], At[m][k], acc[ai][bj][m][n], 0, 0, 0); __builtin_amdgcn_s_setprio(0); } while (0)
; #define PG8_WAIT_V(n) asm volatile("s_waitcnt vmcnt(" #n ")" ::: "memory")
; #define PG8_WAIT_L(n) asm volatile("s_waitcnt lgkmcnt(" #n ")" ::: "memory")
; #define PG8_BAR __builtin_amdgcn_s_barrier()
; #define PG8_SCHED __builtin_amdgcn_sched_barrier(0)
; template <class Epi, class Sched, bool DEFER>
; __device__ __forceinline__ void gemm_fast_core(LAS unsigned char* lds, const GemmP g, const Sched& S, const Epi& E, f32x4 (&acc)[2][2][4][2], Unit& cur) {
;     ...
;             PG8_WAIT_V(8); PG8_WAIT_L(0); PG8_BAR; PG8_MMA(1, 0, At, B0); PG8_MMA(1, 1, At, B1); PG8_BAR; PG8_SCHED;
;             PG8_LDB(B0, 1, 0); PG8_LDB(B1, 1, 1); PG8_SCHED; PG8_LDA(At, 1, 0); PG8_STAGE(PG8_SA(0, 1), a2 + hstepA, voffA);
;             PG8_WAIT_V(8); PG8_WAIT_L(0); PG8_BAR; PG8_MMA(0, 0, At, B0); PG8_MMA(0, 1, At, B1); PG8_BAR; PG8_SCHED;
;             PG8_LDA(At, 1, 1); PG8_STAGE(PG8_SB(1, 0), b3, voffB); PG8_STAGE(PG8_SB(1, 1), b3 + hstepB, voffB); PG8_STAGE(PG8_SA(1, 0), a3, voffA);
;             PG8_WAIT_V(8); PG8_WAIT_L(0); PG8_BAR; PG8_MMA(1, 0, At, B0); PG8_MMA(1, 1, At, B1); PG8_BAR; PG8_SCHED;
	s_setprio 1
	s_waitcnt lgkmcnt(0)
	v_mfma_f32_16x16x32_bf16 v[60:63], v[136:139], v[174:177], 0
	v_mfma_f32_16x16x32_bf16 v[56:59], v[144:147], v[174:177], 0
	v_mfma_f32_16x16x32_bf16 v[44:47], v[136:139], v[182:185], 0
	v_mfma_f32_16x16x32_bf16 v[40:43], v[144:147], v[182:185], 0
	v_mfma_f32_16x16x32_bf16 v[28:31], v[136:139], v[196:199], 0
	v_mfma_f32_16x16x32_bf16 v[24:27], v[144:147], v[196:199], 0
	v_mfma_f32_16x16x32_bf16 v[12:15], v[136:139], v[204:207], 0
	v_mfma_f32_16x16x32_bf16 v[8:11], v[144:147], v[204:207], 0
	v_mfma_f32_16x16x32_bf16 v[60:63], v[140:143], v[178:181], v[60:63]
	v_mfma_f32_16x16x32_bf16 v[56:59], v[154:157], v[178:181], v[56:59]
	v_mfma_f32_16x16x32_bf16 v[44:47], v[140:143], v[192:195], v[44:47]
	v_mfma_f32_16x16x32_bf16 v[40:43], v[154:157], v[192:195], v[40:43]
	v_mfma_f32_16x16x32_bf16 v[28:31], v[140:143], v[200:203], v[28:31]
	v_mfma_f32_16x16x32_bf16 v[24:27], v[154:157], v[200:203], v[24:27]
	v_mfma_f32_16x16x32_bf16 v[12:15], v[140:143], v[208:211], v[12:15]
	v_mfma_f32_16x16x32_bf16 v[8:11], v[154:157], v[208:211], v[8:11]
	s_setprio 0
	s_setprio 1
	v_mfma_f32_16x16x32_bf16 v[52:55], v[158:161], v[174:177], 0
	v_mfma_f32_16x16x32_bf16 v[48:51], v[166:169], v[174:177], 0
	v_mfma_f32_16x16x32_bf16 v[36:39], v[158:161], v[182:185], 0
	v_mfma_f32_16x16x32_bf16 v[32:35], v[166:169], v[182:185], 0
	v_mfma_f32_16x16x32_bf16 v[20:23], v[158:161], v[196:199], 0
	v_mfma_f32_16x16x32_bf16 v[16:19], v[166:169], v[196:199], 0
	v_mfma_f32_16x16x32_bf16 v[4:7], v[158:161], v[204:207], 0
	v_mfma_f32_16x16x32_bf16 v[0:3], v[166:169], v[204:207], 0
	v_mfma_f32_16x16x32_bf16 v[52:55], v[162:165], v[178:181], v[52:55]
	v_mfma_f32_16x16x32_bf16 v[48:51], v[170:173], v[178:181], v[48:51]
	v_mfma_f32_16x16x32_bf16 v[36:39], v[162:165], v[192:195], v[36:39]
	v_mfma_f32_16x16x32_bf16 v[32:35], v[170:173], v[192:195], v[32:35]
	v_mfma_f32_16x16x32_bf16 v[20:23], v[162:165], v[200:203], v[20:23]
	v_mfma_f32_16x16x32_bf16 v[16:19], v[170:173], v[200:203], v[16:19]
	v_mfma_f32_16x16x32_bf16 v[4:7], v[162:165], v[208:211], v[4:7]
	v_mfma_f32_16x16x32_bf16 v[0:3], v[170:173], v[208:211], v[0:3]
	s_setprio 0
	s_barrier
	s_add_i32 s49, 0, 0x18000
	s_add_i32 s50, 0, 0x1c000
	v_add_u32_e32 v154, s49, v149
	v_add_u32_e32 v170, s50, v149
	ds_read_b128 v[136:139], v154
	ds_read_b128 v[140:143], v154 offset:1024
	ds_read_b128 v[144:147], v154 offset:2048
	ds_read_b128 v[154:157], v154 offset:3072
	ds_read_b128 v[158:161], v170
	ds_read_b128 v[162:165], v170 offset:1024
	ds_read_b128 v[166:169], v170 offset:2048
	ds_read_b128 v[170:173], v170 offset:3072
	s_add_u32 s36, s36, 0x40000
	s_addc_u32 s37, s37, 0
	s_mov_b32 m0, s41
	v_lshl_add_u64 v[216:217], s[36:37], 0, v[128:129]
	ds_read_b128 v[174:177], v153 offset:32768
	ds_read_b128 v[178:181], v153 offset:33792
	ds_read_b128 v[182:185], v153 offset:34816
	ds_read_b128 v[192:195], v153 offset:35840
	ds_read_b128 v[196:199], v153 offset:36864
	ds_read_b128 v[200:203], v153 offset:37888
	ds_read_b128 v[204:207], v153 offset:38912
	ds_read_b128 v[208:211], v153 offset:39936
	global_load_lds_dwordx4 v[216:217], off
	v_lshl_add_u64 v[216:217], s[36:37], 0, v[130:131]
	s_mov_b32 m0, s42
	s_nop 0
	global_load_lds_dwordx4 v[216:217], off
	s_waitcnt vmcnt(8)
	s_waitcnt lgkmcnt(0)
	s_barrier
	s_setprio 1
	s_waitcnt lgkmcnt(0)
	v_mfma_f32_16x16x32_bf16 v[124:127], v[136:139], v[174:177], v[124:127]
	v_mfma_f32_16x16x32_bf16 v[120:123], v[144:147], v[174:177], v[120:123]
	v_mfma_f32_16x16x32_bf16 v[108:111], v[136:139], v[182:185], v[108:111]
	v_mfma_f32_16x16x32_bf16 v[104:107], v[144:147], v[182:185], v[104:107]
	v_mfma_f32_16x16x32_bf16 v[92:95], v[136:139], v[196:199], v[92:95]
	v_mfma_f32_16x16x32_bf16 v[88:91], v[144:147], v[196:199], v[88:91]
	v_mfma_f32_16x16x32_bf16 v[76:79], v[136:139], v[204:207], v[76:79]
	v_mfma_f32_16x16x32_bf16 v[72:75], v[144:147], v[204:207], v[72:75]
	v_mfma_f32_16x16x32_bf16 v[124:127], v[140:143], v[178:181], v[124:127]
	v_mfma_f32_16x16x32_bf16 v[120:123], v[154:157], v[178:181], v[120:123]
	v_mfma_f32_16x16x32_bf16 v[108:111], v[140:143], v[192:195], v[108:111]
	v_mfma_f32_16x16x32_bf16 v[104:107], v[154:157], v[192:195], v[104:107]
	v_mfma_f32_16x16x32_bf16 v[92:95], v[140:143], v[200:203], v[92:95]
	v_mfma_f32_16x16x32_bf16 v[88:91], v[154:157], v[200:203], v[88:91]
	v_mfma_f32_16x16x32_bf16 v[76:79], v[140:143], v[208:211], v[76:79]
	v_mfma_f32_16x16x32_bf16 v[72:75], v[154:157], v[208:211], v[72:75]
	s_setprio 0
	s_setprio 1
	v_mfma_f32_16x16x32_bf16 v[116:119], v[158:161], v[174:177], v[116:119]
	v_mfma_f32_16x16x32_bf16 v[112:115], v[166:169], v[174:177], v[112:115]
	v_mfma_f32_16x16x32_bf16 v[100:103], v[158:161], v[182:185], v[100:103]
	v_mfma_f32_16x16x32_bf16 v[96:99], v[166:169], v[182:185], v[96:99]
	v_mfma_f32_16x16x32_bf16 v[84:87], v[158:161], v[196:199], v[84:87]
	v_mfma_f32_16x16x32_bf16 v[80:83], v[166:169], v[196:199], v[80:83]
	v_mfma_f32_16x16x32_bf16 v[68:71], v[158:161], v[204:207], v[68:71]
	v_mfma_f32_16x16x32_bf16 v[64:67], v[166:169], v[204:207], v[64:67]
	v_mfma_f32_16x16x32_bf16 v[116:119], v[162:165], v[178:181], v[116:119]
	v_mfma_f32_16x16x32_bf16 v[112:115], v[170:173], v[178:181], v[112:115]
	v_mfma_f32_16x16x32_bf16 v[100:103], v[162:165], v[192:195], v[100:103]
	v_mfma_f32_16x16x32_bf16 v[96:99], v[170:173], v[192:195], v[96:99]
	v_mfma_f32_16x16x32_bf16 v[84:87], v[162:165], v[200:203], v[84:87]
	v_mfma_f32_16x16x32_bf16 v[80:83], v[170:173], v[200:203], v[80:83]
	v_mfma_f32_16x16x32_bf16 v[68:71], v[162:165], v[208:211], v[68:71]
	v_mfma_f32_16x16x32_bf16 v[64:67], v[170:173], v[208:211], v[64:67]
	s_setprio 0
	s_barrier
; #define PG8_STAGE(bufoff, gbase, voff) do { _Pragma("unroll") for (int _i = 0; _i < 2; ++_i) \
;         __builtin_amdgcn_global_load_lds((const unsigned*)((const char*)(gbase) + (voff)[_i]), (LAS unsigned*)(lds + (bufoff) + ldsw + _i * 8192), 16, 0, 0); } while (0)
; #define PG8_LDA(dst, b, h) do { _Pragma("unroll") for (int m = 0; m < 4; ++m) _Pragma("unroll") for (int k = 0; k < 2; ++k) dst[m][k] = *(const LAS bf16x8*)(lds + PG8_SA(b, h) + aoff + m * 2048 + k * 1024); } while (0)
; #define PG8_MMA(ai, bj, At, Bt) do { __builtin_amdgcn_s_setprio(1); _Pragma("unroll") for (int m = 0; m < 4; ++m) _Pragma("unroll") for (int n = 0; n < 2; ++n) _Pragma("unroll") for (int k = 0; k < 2; ++k) \
;         acc[ai][bj][m][n] = __builtin_amdgcn_mfma_f32_16x16x32_bf16(Bt[n][k], At[m][k], acc[ai][bj][m][n], 0, 0, 0); __builtin_amdgcn_s_setprio(0); } while (0)
; #define PG8_WAIT_V(n) asm volatile("s_waitcnt vmcnt(" #n ")" ::: "memory")
; #define PG8_WAIT_L(n) asm volatile("s_waitcnt lgkmcnt(" #n ")" ::: "memory")
; #define PG8_BAR __builtin_amdgcn_s_barrier()
; #define PG8_SCHED __builtin_amdgcn_sched_barrier(0)
; template <class Epi, class Sched, bool DEFER>
; __device__ __forceinline__ void gemm_fast_core(LAS unsigned char* lds, const GemmP g, const Sched& S, const Epi& E, f32x4 (&acc)[2][2][4][2], Unit& cur) {
;     ...
;         for (int t = 0; t < nt; t += 2) {
;     ...
;             PG8_LDA(At, 1, 1); PG8_STAGE(PG8_SB(1, 0), b3, voffB); PG8_STAGE(PG8_SB(1, 1), b3 + hstepB, voffB); PG8_STAGE(PG8_SA(1, 0), a3, voffA);
;             PG8_WAIT_V(8); PG8_WAIT_L(0); PG8_BAR; PG8_MMA(1, 0, At, B0); PG8_MMA(1, 1, At, B1); PG8_BAR; PG8_SCHED;
	s_add_i32 s36, s49, s38
	v_lshl_add_u64 v[186:187], v[186:187], 0, s[6:7]
	s_mov_b32 m0, s36
	ds_read_b128 v[174:177], v153 offset:49152
	ds_read_b128 v[178:181], v153 offset:50176
	ds_read_b128 v[182:185], v153 offset:51200
	ds_read_b128 v[192:195], v153 offset:52224
	ds_read_b128 v[196:199], v153 offset:53248
	ds_read_b128 v[200:203], v153 offset:54272
	ds_read_b128 v[204:207], v153 offset:55296
	ds_read_b128 v[208:211], v153 offset:56320
	global_load_lds_dwordx4 v[186:187], off
	s_add_i32 m0, s36, 0x2000
	s_add_u32 s34, s34, 0x40080
	v_lshl_add_u64 v[186:187], v[190:191], 0, s[6:7]
	s_addc_u32 s35, s35, 0
	s_add_i32 s36, s50, s38
	global_load_lds_dwordx4 v[186:187], off
	v_lshl_add_u64 v[186:187], s[34:35], 0, v[128:129]
	s_mov_b32 m0, s36
	s_nop 0
	global_load_lds_dwordx4 v[186:187], off
	v_lshl_add_u64 v[186:187], s[34:35], 0, v[130:131]
	s_add_i32 m0, s36, 0x2000
	s_nop 0
	global_load_lds_dwordx4 v[186:187], off
	v_lshl_add_u64 v[186:187], v[212:213], 0, s[6:7]
	s_mov_b32 m0, s43
	s_nop 0
	global_load_lds_dwordx4 v[186:187], off
	v_lshl_add_u64 v[186:187], v[214:215], 0, s[6:7]
	s_mov_b32 m0, s44
	s_nop 0
	global_load_lds_dwordx4 v[186:187], off
	s_waitcnt vmcnt(8)
	s_waitcnt lgkmcnt(0)
	s_barrier
	s_setprio 1
	s_waitcnt lgkmcnt(0)
	v_mfma_f32_16x16x32_bf16 v[60:63], v[136:139], v[174:177], v[60:63]
	v_mfma_f32_16x16x32_bf16 v[56:59], v[144:147], v[174:177], v[56:59]
	v_mfma_f32_16x16x32_bf16 v[44:47], v[136:139], v[182:185], v[44:47]
	v_mfma_f32_16x16x32_bf16 v[40:43], v[144:147], v[182:185], v[40:43]
	v_mfma_f32_16x16x32_bf16 v[28:31], v[136:139], v[196:199], v[28:31]
	v_mfma_f32_16x16x32_bf16 v[24:27], v[144:147], v[196:199], v[24:27]
	v_mfma_f32_16x16x32_bf16 v[12:15], v[136:139], v[204:207], v[12:15]
	v_mfma_f32_16x16x32_bf16 v[8:11], v[144:147], v[204:207], v[8:11]
	v_mfma_f32_16x16x32_bf16 v[60:63], v[140:143], v[178:181], v[60:63]
	v_mfma_f32_16x16x32_bf16 v[56:59], v[154:157], v[178:181], v[56:59]
	v_mfma_f32_16x16x32_bf16 v[44:47], v[140:143], v[192:195], v[44:47]
	v_mfma_f32_16x16x32_bf16 v[40:43], v[154:157], v[192:195], v[40:43]
	v_mfma_f32_16x16x32_bf16 v[28:31], v[140:143], v[200:203], v[28:31]
	v_mfma_f32_16x16x32_bf16 v[24:27], v[154:157], v[200:203], v[24:27]
	v_mfma_f32_16x16x32_bf16 v[12:15], v[140:143], v[208:211], v[12:15]
	v_mfma_f32_16x16x32_bf16 v[8:11], v[154:157], v[208:211], v[8:11]
	s_setprio 0
	s_setprio 1
	v_mfma_f32_16x16x32_bf16 v[52:55], v[158:161], v[174:177], v[52:55]
	v_mfma_f32_16x16x32_bf16 v[48:51], v[166:169], v[174:177], v[48:51]
	v_mfma_f32_16x16x32_bf16 v[36:39], v[158:161], v[182:185], v[36:39]
	v_mfma_f32_16x16x32_bf16 v[32:35], v[166:169], v[182:185], v[32:35]
	v_mfma_f32_16x16x32_bf16 v[20:23], v[158:161], v[196:199], v[20:23]
	v_mfma_f32_16x16x32_bf16 v[16:19], v[166:169], v[196:199], v[16:19]
	v_mfma_f32_16x16x32_bf16 v[4:7], v[158:161], v[204:207], v[4:7]
	v_mfma_f32_16x16x32_bf16 v[0:3], v[166:169], v[204:207], v[0:3]
	v_mfma_f32_16x16x32_bf16 v[52:55], v[162:165], v[178:181], v[52:55]
	v_mfma_f32_16x16x32_bf16 v[48:51], v[170:173], v[178:181], v[48:51]
	v_mfma_f32_16x16x32_bf16 v[36:39], v[162:165], v[192:195], v[36:39]
	v_mfma_f32_16x16x32_bf16 v[32:35], v[170:173], v[192:195], v[32:35]
	v_mfma_f32_16x16x32_bf16 v[20:23], v[162:165], v[200:203], v[20:23]
	v_mfma_f32_16x16x32_bf16 v[16:19], v[170:173], v[200:203], v[16:19]
	v_mfma_f32_16x16x32_bf16 v[4:7], v[162:165], v[208:211], v[4:7]
	v_mfma_f32_16x16x32_bf16 v[0:3], v[170:173], v[208:211], v[0:3]
	s_setprio 0
	s_barrier
	s_add_i32 s48, s48, 2
	s_add_u32 s30, s30, 0x100
	s_addc_u32 s31, s31, 0
	s_add_u32 s33, s33, 0x100
	s_addc_u32 s47, s47, 0
	s_cmp_gt_u32 s48, 13
	s_cbranch_scc0 .LBB0_1410
	s_branch .Lpeel_p6_done
	.p2align 6

; #define PG8_BAR __builtin_amdgcn_s_barrier()
; template <class Epi, class Sched, bool DEFER>
; __device__ __forceinline__ void gemm_fast_core(LAS unsigned char* lds, const GemmP g, const Sched& S, const Epi& E, f32x4 (&acc)[2][2][4][2], Unit& cur) {
;     ...
;         if (wr == 0) PG8_BAR;
.Lpeel_p6_done:
	s_and_b64 vcc, exec, s[8:9]
	s_cbranch_vccz .LBB0_1413
	s_barrier

;     __device__ __forceinline__ bool next(int i, Unit& u) const { return decode(i * G + c, u); }
; #define PG8_STAGE(bufoff, gbase, voff) do { _Pragma("unroll") for (int _i = 0; _i < 2; ++_i) \
;         __builtin_amdgcn_global_load_lds((const unsigned*)((const char*)(gbase) + (voff)[_i]), (LAS unsigned*)(lds + (bufoff) + ldsw + _i * 8192), 16, 0, 0); } while (0)
; #define PG8_LDA(dst, b, h) do { _Pragma("unroll") for (int m = 0; m < 4; ++m) _Pragma("unroll") for (int k = 0; k < 2; ++k) dst[m][k] = *(const LAS bf16x8*)(lds + PG8_SA(b, h) + aoff + m * 2048 + k * 1024); } while (0)
; #define PG8_LDB(dst, b, h) do { _Pragma("unroll") for (int n = 0; n < 2; ++n) _Pragma("unroll") for (int k = 0; k < 2; ++k) dst[n][k] = *(const LAS bf16x8*)(lds + PG8_SB(b, h) + boff + n * 2048 + k * 1024); } while (0)
; #define PG8_WAIT_V(n) asm volatile("s_waitcnt vmcnt(" #n ")" ::: "memory")
; #define PG8_WAIT_L(n) asm volatile("s_waitcnt lgkmcnt(" #n ")" ::: "memory")
; #define PG8_BAR __builtin_amdgcn_s_barrier()
; #define PG8_SCHED __builtin_amdgcn_sched_barrier(0)
; template <class Epi, class Sched, bool DEFER>
; __device__ __forceinline__ void gemm_fast_core(LAS unsigned char* lds, const GemmP g, const Sched& S, const Epi& E, f32x4 (&acc)[2][2][4][2], Unit& cur) {
;     ...
;         const bool has_next = S.next(ui + 1, nxt);
;         const char* nA = has_next ? (const char*)g.aptr(nxt) : cA; const char* nB = has_next ? (const char*)g.bptr(nxt) : cB;
;         for (int t = 0; t < nt; t += 2) {
;             const bool last = (t == nt - 2);
;             const char* a1 = cA + (size_t)(t + 1) * kstep;
;             const char* a2 = last ? nA : cA + (size_t)(t + 2) * kstep; const char* b2 = last ? nB : cB + (size_t)(t + 2) * kstep;
;             const char* a3 = a2 + kstep; const char* b3 = b2 + kstep;
;             PG8_LDB(B0, 0, 0); PG8_LDB(B1, 0, 1); PG8_SCHED; PG8_LDA(At, 0, 0); PG8_STAGE(PG8_SA(1, 1), a1 + hstepA, voffA);
;             PG8_WAIT_V(8); PG8_WAIT_L(0); PG8_BAR; PG8_MMA(0, 0, At, B0); PG8_MMA(0, 1, At, B1); PG8_BAR; PG8_SCHED;
;             PG8_LDA(At, 0, 1); PG8_STAGE(PG8_SB(0, 0), b2, voffB); PG8_STAGE(PG8_SB(0, 1), b2 + hstepB, voffB); PG8_STAGE(PG8_SA(0, 0), a2, voffA);
;             PG8_WAIT_V(8); PG8_WAIT_L(0); PG8_BAR; PG8_MMA(1, 0, At, B0); PG8_MMA(1, 1, At, B1); PG8_BAR; PG8_SCHED;
.LBB0_1885:
	s_add_u32 s45, s20, 0x100
	s_addc_u32 s46, s21, 0
	s_mov_b32 s47, -2
	.p2align 6
	ds_read_b128 v[142:145], v136
	ds_read_b128 v[146:149], v136 offset:1024
	ds_read_b128 v[150:153], v136 offset:2048
	ds_read_b128 v[154:157], v136 offset:3072
	ds_read_b128 v[158:161], v137
	ds_read_b128 v[162:165], v137 offset:1024
	ds_read_b128 v[166:169], v137 offset:2048
	ds_read_b128 v[170:173], v137 offset:3072
	s_add_u32 s20, s18, 0x100
	s_addc_u32 s21, s19, 0
	s_cmpk_eq_i32 s47, 0x54
	s_cselect_b32 s25, s15, s21
	s_cselect_b32 s24, s14, s20
	s_cselect_b32 s23, s17, s46
	s_cselect_b32 s22, s16, s45
	s_mov_b32 m0, s36
	v_lshl_add_u64 v[186:187], s[18:19], 0, v[132:133]
	ds_read_b128 v[174:177], v138
	ds_read_b128 v[178:181], v138 offset:1024
	ds_read_b128 v[182:185], v138 offset:2048
	ds_read_b128 v[196:199], v138 offset:3072
	ds_read_b128 v[200:203], v138 offset:4096
	ds_read_b128 v[204:207], v138 offset:5120
	ds_read_b128 v[208:211], v138 offset:6144
	ds_read_b128 v[212:215], v138 offset:7168
	global_load_lds_dwordx4 v[186:187], off
	v_lshl_add_u64 v[186:187], s[18:19], 0, v[134:135]
	s_mov_b32 m0, s37
	s_nop 0
	global_load_lds_dwordx4 v[186:187], off
	s_waitcnt vmcnt(8)
	s_waitcnt lgkmcnt(0)
	s_barrier
	s_setprio 1
	s_waitcnt lgkmcnt(0)
	v_mfma_f32_16x16x32_bf16 v[128:131], v[142:145], v[174:177], 0
	v_mfma_f32_16x16x32_bf16 v[124:127], v[150:153], v[174:177], 0
	v_mfma_f32_16x16x32_bf16 v[112:115], v[142:145], v[182:185], 0
	v_mfma_f32_16x16x32_bf16 v[108:111], v[150:153], v[182:185], 0
	v_mfma_f32_16x16x32_bf16 v[96:99], v[142:145], v[200:203], 0
	v_mfma_f32_16x16x32_bf16 v[92:95], v[150:153], v[200:203], 0
	v_mfma_f32_16x16x32_bf16 v[80:83], v[142:145], v[208:211], 0
	v_mfma_f32_16x16x32_bf16 v[76:79], v[150:153], v[208:211], 0
	v_mfma_f32_16x16x32_bf16 v[128:131], v[146:149], v[178:181], v[128:131]
	v_mfma_f32_16x16x32_bf16 v[124:127], v[154:157], v[178:181], v[124:127]
	v_mfma_f32_16x16x32_bf16 v[112:115], v[146:149], v[196:199], v[112:115]
	v_mfma_f32_16x16x32_bf16 v[108:111], v[154:157], v[196:199], v[108:111]
	v_mfma_f32_16x16x32_bf16 v[96:99], v[146:149], v[204:207], v[96:99]
	v_mfma_f32_16x16x32_bf16 v[92:95], v[154:157], v[204:207], v[92:95]
	v_mfma_f32_16x16x32_bf16 v[80:83], v[146:149], v[212:215], v[80:83]
	v_mfma_f32_16x16x32_bf16 v[76:79], v[154:157], v[212:215], v[76:79]
	s_setprio 0
	s_setprio 1
	v_mfma_f32_16x16x32_bf16 v[120:123], v[158:161], v[174:177], 0
	v_mfma_f32_16x16x32_bf16 v[116:119], v[166:169], v[174:177], 0
	v_mfma_f32_16x16x32_bf16 v[104:107], v[158:161], v[182:185], 0
	v_mfma_f32_16x16x32_bf16 v[100:103], v[166:169], v[182:185], 0
	v_mfma_f32_16x16x32_bf16 v[88:91], v[158:161], v[200:203], 0
	v_mfma_f32_16x16x32_bf16 v[84:87], v[166:169], v[200:203], 0
	v_mfma_f32_16x16x32_bf16 v[72:75], v[158:161], v[208:211], 0
	v_mfma_f32_16x16x32_bf16 v[68:71], v[166:169], v[208:211], 0
	v_mfma_f32_16x16x32_bf16 v[120:123], v[162:165], v[178:181], v[120:123]
	v_mfma_f32_16x16x32_bf16 v[116:119], v[170:173], v[178:181], v[116:119]
	v_mfma_f32_16x16x32_bf16 v[104:107], v[162:165], v[196:199], v[104:107]
	v_mfma_f32_16x16x32_bf16 v[100:103], v[170:173], v[196:199], v[100:103]
	v_mfma_f32_16x16x32_bf16 v[88:91], v[162:165], v[204:207], v[88:91]
	v_mfma_f32_16x16x32_bf16 v[84:87], v[170:173], v[204:207], v[84:87]
	v_mfma_f32_16x16x32_bf16 v[72:75], v[162:165], v[212:215], v[72:75]
	v_mfma_f32_16x16x32_bf16 v[68:71], v[170:173], v[212:215], v[68:71]
	s_setprio 0
	s_barrier
	s_mov_b32 m0, s38
	v_lshl_add_u64 v[186:187], s[22:23], 0, v[64:65]
	s_add_u32 s18, s22, 0x160000
	ds_read_b128 v[174:177], v138 offset:16384
	ds_read_b128 v[178:181], v138 offset:17408
	ds_read_b128 v[182:185], v138 offset:18432
	ds_read_b128 v[196:199], v138 offset:19456
	ds_read_b128 v[200:203], v138 offset:20480
	ds_read_b128 v[204:207], v138 offset:21504
	ds_read_b128 v[208:211], v138 offset:22528
	ds_read_b128 v[212:215], v138 offset:23552
	global_load_lds_dwordx4 v[186:187], off
	v_lshl_add_u64 v[216:217], s[22:23], 0, v[66:67]
	s_mov_b32 m0, s39
	s_addc_u32 s19, s23, 0
	global_load_lds_dwordx4 v[216:217], off
	v_lshl_add_u64 v[218:219], s[18:19], 0, v[64:65]
	s_mov_b32 m0, s40
	v_lshl_add_u64 v[220:221], s[24:25], 0, v[66:67]
	global_load_lds_dwordx4 v[218:219], off
	v_lshl_add_u64 v[218:219], s[18:19], 0, v[66:67]
	s_mov_b32 m0, s41
	s_nop 0
	global_load_lds_dwordx4 v[218:219], off
	v_lshl_add_u64 v[218:219], s[24:25], 0, v[64:65]
	s_mov_b32 m0, s27
	s_nop 0
	global_load_lds_dwordx4 v[218:219], off
	s_mov_b32 m0, s28
	s_nop 0
	global_load_lds_dwordx4 v[220:221], off
	s_waitcnt vmcnt(8)
	s_waitcnt lgkmcnt(0)
	s_barrier
; #define PG8_STAGE(bufoff, gbase, voff) do { _Pragma("unroll") for (int _i = 0; _i < 2; ++_i) \
;         __builtin_amdgcn_global_load_lds((const unsigned*)((const char*)(gbase) + (voff)[_i]), (LAS unsigned*)(lds + (bufoff) + ldsw + _i * 8192), 16, 0, 0); } while (0)
; #define PG8_LDA(dst, b, h) do { _Pragma("unroll") for (int m = 0; m < 4; ++m) _Pragma("unroll") for (int k = 0; k < 2; ++k) dst[m][k] = *(const LAS bf16x8*)(lds + PG8_SA(b, h) + aoff + m * 2048 + k * 1024); } while (0)
; #define PG8_LDB(dst, b, h) do { _Pragma("unroll") for (int n = 0; n < 2; ++n) _Pragma("unroll") for (int k = 0; k < 2; ++k) dst[n][k] = *(const LAS bf16x8*)(lds + PG8_SB(b, h) + boff + n * 2048 + k * 1024); } while (0)
; #define PG8_MMA(ai, bj, At, Bt) do { __builtin_amdgcn_s_setprio(1); _Pragma("unroll") for (int m = 0; m < 4; ++m) _Pragma("unroll") for (int n = 0; n < 2; ++n) _Pragma("unroll") for (int k = 0; k < 2; ++k) \
;         acc[ai][bj][m][n] = __builtin_amdgcn_mfma_f32_16x16x32_bf16(Bt[n][k], At[m][k], acc[ai][bj][m][n], 0, 0, 0); __builtin_amdgcn_s_setprio(0); } while (0)
; #define PG8_WAIT_V(n) asm volatile("s_waitcnt vmcnt(" #n ")" ::: "memory")
; #define PG8_WAIT_L(n) asm volatile("s_waitcnt lgkmcnt(" #n ")" ::: "memory")
; #define PG8_BAR __builtin_amdgcn_s_barrier()
; #define PG8_SCHED __builtin_amdgcn_sched_barrier(0)
; template <class Epi, class Sched, bool DEFER>
; __device__ __forceinline__ void gemm_fast_core(LAS unsigned char* lds, const GemmP g, const Sched& S, const Epi& E, f32x4 (&acc)[2][2][4][2], Unit& cur) {
;     ...
;             PG8_WAIT_V(8); PG8_WAIT_L(0); PG8_BAR; PG8_MMA(1, 0, At, B0); PG8_MMA(1, 1, At, B1); PG8_BAR; PG8_SCHED;
;             PG8_LDB(B0, 1, 0); PG8_LDB(B1, 1, 1); PG8_SCHED; PG8_LDA(At, 1, 0); PG8_STAGE(PG8_SA(0, 1), a2 + hstepA, voffA);
;             PG8_WAIT_V(8); PG8_WAIT_L(0); PG8_BAR; PG8_MMA(0, 0, At, B0); PG8_MMA(0, 1, At, B1); PG8_BAR; PG8_SCHED;
;             PG8_LDA(At, 1, 1); PG8_STAGE(PG8_SB(1, 0), b3, voffB); PG8_STAGE(PG8_SB(1, 1), b3 + hstepB, voffB); PG8_STAGE(PG8_SA(1, 0), a3, voffA);
;             PG8_WAIT_V(8); PG8_WAIT_L(0); PG8_BAR; PG8_MMA(1, 0, At, B0); PG8_MMA(1, 1, At, B1); PG8_BAR; PG8_SCHED;
	s_setprio 1
	s_waitcnt lgkmcnt(0)
	v_mfma_f32_16x16x32_bf16 v[60:63], v[142:145], v[174:177], 0
	v_mfma_f32_16x16x32_bf16 v[56:59], v[150:153], v[174:177], 0
	v_mfma_f32_16x16x32_bf16 v[44:47], v[142:145], v[182:185], 0
	v_mfma_f32_16x16x32_bf16 v[40:43], v[150:153], v[182:185], 0
	v_mfma_f32_16x16x32_bf16 v[28:31], v[142:145], v[200:203], 0
	v_mfma_f32_16x16x32_bf16 v[24:27], v[150:153], v[200:203], 0
	v_mfma_f32_16x16x32_bf16 v[12:15], v[142:145], v[208:211], 0
	v_mfma_f32_16x16x32_bf16 v[8:11], v[150:153], v[208:211], 0
	v_mfma_f32_16x16x32_bf16 v[60:63], v[146:149], v[178:181], v[60:63]
	v_mfma_f32_16x16x32_bf16 v[56:59], v[154:157], v[178:181], v[56:59]
	v_mfma_f32_16x16x32_bf16 v[44:47], v[146:149], v[196:199], v[44:47]
	v_mfma_f32_16x16x32_bf16 v[40:43], v[154:157], v[196:199], v[40:43]
	v_mfma_f32_16x16x32_bf16 v[28:31], v[146:149], v[204:207], v[28:31]
	v_mfma_f32_16x16x32_bf16 v[24:27], v[154:157], v[204:207], v[24:27]
	v_mfma_f32_16x16x32_bf16 v[12:15], v[146:149], v[212:215], v[12:15]
	v_mfma_f32_16x16x32_bf16 v[8:11], v[154:157], v[212:215], v[8:11]
	s_setprio 0
	s_setprio 1
	v_mfma_f32_16x16x32_bf16 v[52:55], v[158:161], v[174:177], 0
	v_mfma_f32_16x16x32_bf16 v[48:51], v[166:169], v[174:177], 0
	v_mfma_f32_16x16x32_bf16 v[36:39], v[158:161], v[182:185], 0
	v_mfma_f32_16x16x32_bf16 v[32:35], v[166:169], v[182:185], 0
	v_mfma_f32_16x16x32_bf16 v[20:23], v[158:161], v[200:203], 0
	v_mfma_f32_16x16x32_bf16 v[16:19], v[166:169], v[200:203], 0
	v_mfma_f32_16x16x32_bf16 v[4:7], v[158:161], v[208:211], 0
	v_mfma_f32_16x16x32_bf16 v[0:3], v[166:169], v[208:211], 0
	v_mfma_f32_16x16x32_bf16 v[52:55], v[162:165], v[178:181], v[52:55]
	v_mfma_f32_16x16x32_bf16 v[48:51], v[170:173], v[178:181], v[48:51]
	v_mfma_f32_16x16x32_bf16 v[36:39], v[162:165], v[196:199], v[36:39]
	v_mfma_f32_16x16x32_bf16 v[32:35], v[170:173], v[196:199], v[32:35]
	v_mfma_f32_16x16x32_bf16 v[20:23], v[162:165], v[204:207], v[20:23]
	v_mfma_f32_16x16x32_bf16 v[16:19], v[170:173], v[204:207], v[16:19]
	v_mfma_f32_16x16x32_bf16 v[4:7], v[162:165], v[212:215], v[4:7]
	v_mfma_f32_16x16x32_bf16 v[0:3], v[170:173], v[212:215], v[0:3]
	s_setprio 0
	s_barrier
	ds_read_b128 v[142:145], v139
	ds_read_b128 v[146:149], v139 offset:1024
	ds_read_b128 v[150:153], v139 offset:2048
	ds_read_b128 v[154:157], v139 offset:3072
	ds_read_b128 v[158:161], v140
	ds_read_b128 v[162:165], v140 offset:1024
	ds_read_b128 v[166:169], v140 offset:2048
	ds_read_b128 v[170:173], v140 offset:3072
	s_add_u32 s18, s24, 0x160000
	s_addc_u32 s19, s25, 0
	s_mov_b32 m0, s29
	v_lshl_add_u64 v[222:223], s[18:19], 0, v[64:65]
	ds_read_b128 v[174:177], v138 offset:32768
	ds_read_b128 v[178:181], v138 offset:33792
	ds_read_b128 v[182:185], v138 offset:34816
	ds_read_b128 v[196:199], v138 offset:35840
	ds_read_b128 v[200:203], v138 offset:36864
	ds_read_b128 v[204:207], v138 offset:37888
	ds_read_b128 v[208:211], v138 offset:38912
	ds_read_b128 v[212:215], v138 offset:39936
	global_load_lds_dwordx4 v[222:223], off
	v_lshl_add_u64 v[222:223], s[18:19], 0, v[66:67]
	s_mov_b32 m0, s30
	s_nop 0
	global_load_lds_dwordx4 v[222:223], off
	s_waitcnt vmcnt(8)
	s_waitcnt lgkmcnt(0)
	s_barrier
	s_setprio 1
	s_waitcnt lgkmcnt(0)
	v_mfma_f32_16x16x32_bf16 v[128:131], v[142:145], v[174:177], v[128:131]
	v_mfma_f32_16x16x32_bf16 v[124:127], v[150:153], v[174:177], v[124:127]
	v_mfma_f32_16x16x32_bf16 v[112:115], v[142:145], v[182:185], v[112:115]
	v_mfma_f32_16x16x32_bf16 v[108:111], v[150:153], v[182:185], v[108:111]
	v_mfma_f32_16x16x32_bf16 v[96:99], v[142:145], v[200:203], v[96:99]
	v_mfma_f32_16x16x32_bf16 v[92:95], v[150:153], v[200:203], v[92:95]
	v_mfma_f32_16x16x32_bf16 v[80:83], v[142:145], v[208:211], v[80:83]
	v_mfma_f32_16x16x32_bf16 v[76:79], v[150:153], v[208:211], v[76:79]
	v_mfma_f32_16x16x32_bf16 v[128:131], v[146:149], v[178:181], v[128:131]
	v_mfma_f32_16x16x32_bf16 v[124:127], v[154:157], v[178:181], v[124:127]
	v_mfma_f32_16x16x32_bf16 v[112:115], v[146:149], v[196:199], v[112:115]
	v_mfma_f32_16x16x32_bf16 v[108:111], v[154:157], v[196:199], v[108:111]
	v_mfma_f32_16x16x32_bf16 v[96:99], v[146:149], v[204:207], v[96:99]
	v_mfma_f32_16x16x32_bf16 v[92:95], v[154:157], v[204:207], v[92:95]
	v_mfma_f32_16x16x32_bf16 v[80:83], v[146:149], v[212:215], v[80:83]
	v_mfma_f32_16x16x32_bf16 v[76:79], v[154:157], v[212:215], v[76:79]
	s_setprio 0
	s_setprio 1
	v_mfma_f32_16x16x32_bf16 v[120:123], v[158:161], v[174:177], v[120:123]
	v_mfma_f32_16x16x32_bf16 v[116:119], v[166:169], v[174:177], v[116:119]
	v_mfma_f32_16x16x32_bf16 v[104:107], v[158:161], v[182:185], v[104:107]
	v_mfma_f32_16x16x32_bf16 v[100:103], v[166:169], v[182:185], v[100:103]
	v_mfma_f32_16x16x32_bf16 v[88:91], v[158:161], v[200:203], v[88:91]
	v_mfma_f32_16x16x32_bf16 v[84:87], v[166:169], v[200:203], v[84:87]
	v_mfma_f32_16x16x32_bf16 v[72:75], v[158:161], v[208:211], v[72:75]
	v_mfma_f32_16x16x32_bf16 v[68:71], v[166:169], v[208:211], v[68:71]
	v_mfma_f32_16x16x32_bf16 v[120:123], v[162:165], v[178:181], v[120:123]
	v_mfma_f32_16x16x32_bf16 v[116:119], v[170:173], v[178:181], v[116:119]
	v_mfma_f32_16x16x32_bf16 v[104:107], v[162:165], v[196:199], v[104:107]
	v_mfma_f32_16x16x32_bf16 v[100:103], v[170:173], v[196:199], v[100:103]
	v_mfma_f32_16x16x32_bf16 v[88:91], v[162:165], v[204:207], v[88:91]
	v_mfma_f32_16x16x32_bf16 v[84:87], v[170:173], v[204:207], v[84:87]
	v_mfma_f32_16x16x32_bf16 v[72:75], v[162:165], v[212:215], v[72:75]
	v_mfma_f32_16x16x32_bf16 v[68:71], v[170:173], v[212:215], v[68:71]
	s_setprio 0
	s_barrier
; #define PG8_STAGE(bufoff, gbase, voff) do { _Pragma("unroll") for (int _i = 0; _i < 2; ++_i) \
;         __builtin_amdgcn_global_load_lds((const unsigned*)((const char*)(gbase) + (voff)[_i]), (LAS unsigned*)(lds + (bufoff) + ldsw + _i * 8192), 16, 0, 0); } while (0)
; #define PG8_LDA(dst, b, h) do { _Pragma("unroll") for (int m = 0; m < 4; ++m) _Pragma("unroll") for (int k = 0; k < 2; ++k) dst[m][k] = *(const LAS bf16x8*)(lds + PG8_SA(b, h) + aoff + m * 2048 + k * 1024); } while (0)
; #define PG8_MMA(ai, bj, At, Bt) do { __builtin_amdgcn_s_setprio(1); _Pragma("unroll") for (int m = 0; m < 4; ++m) _Pragma("unroll") for (int n = 0; n < 2; ++n) _Pragma("unroll") for (int k = 0; k < 2; ++k) \
;         acc[ai][bj][m][n] = __builtin_amdgcn_mfma_f32_16x16x32_bf16(Bt[n][k], At[m][k], acc[ai][bj][m][n], 0, 0, 0); __builtin_amdgcn_s_setprio(0); } while (0)
; #define PG8_WAIT_V(n) asm volatile("s_waitcnt vmcnt(" #n ")" ::: "memory")
; #define PG8_WAIT_L(n) asm volatile("s_waitcnt lgkmcnt(" #n ")" ::: "memory")
; #define PG8_BAR __builtin_amdgcn_s_barrier()
; #define PG8_SCHED __builtin_amdgcn_sched_barrier(0)
; template <class Epi, class Sched, bool DEFER>
; __device__ __forceinline__ void gemm_fast_core(LAS unsigned char* lds, const GemmP g, const Sched& S, const Epi& E, f32x4 (&acc)[2][2][4][2], Unit& cur) {
;     ...
;         for (int t = 0; t < nt; t += 2) {
;     ...
;             PG8_LDA(At, 1, 1); PG8_STAGE(PG8_SB(1, 0), b3, voffB); PG8_STAGE(PG8_SB(1, 1), b3 + hstepB, voffB); PG8_STAGE(PG8_SA(1, 0), a3, voffA);
;             PG8_WAIT_V(8); PG8_WAIT_L(0); PG8_BAR; PG8_MMA(1, 0, At, B0); PG8_MMA(1, 1, At, B1); PG8_BAR; PG8_SCHED;
	s_mov_b32 m0, s43
	v_lshl_add_u64 v[186:187], v[186:187], 0, s[10:11]
	ds_read_b128 v[174:177], v138 offset:49152
	ds_read_b128 v[178:181], v138 offset:50176
	ds_read_b128 v[182:185], v138 offset:51200
	ds_read_b128 v[196:199], v138 offset:52224
	ds_read_b128 v[200:203], v138 offset:53248
	ds_read_b128 v[204:207], v138 offset:54272
	ds_read_b128 v[208:211], v138 offset:55296
	ds_read_b128 v[212:215], v138 offset:56320
	global_load_lds_dwordx4 v[186:187], off
	s_add_i32 m0, s43, 0x2000
	s_add_u32 s18, s22, 0x160080
	v_lshl_add_u64 v[186:187], v[216:217], 0, s[10:11]
	s_addc_u32 s19, s23, 0
	s_add_i32 s22, s42, s26
	global_load_lds_dwordx4 v[186:187], off
	v_lshl_add_u64 v[186:187], s[18:19], 0, v[64:65]
	s_mov_b32 m0, s22
	s_nop 0
	global_load_lds_dwordx4 v[186:187], off
	v_lshl_add_u64 v[186:187], s[18:19], 0, v[66:67]
	s_add_i32 m0, s22, 0x2000
	s_nop 0
	global_load_lds_dwordx4 v[186:187], off
	v_lshl_add_u64 v[186:187], v[218:219], 0, s[10:11]
	s_mov_b32 m0, s34
	s_nop 0
	global_load_lds_dwordx4 v[186:187], off
	v_lshl_add_u64 v[186:187], v[220:221], 0, s[10:11]
	s_mov_b32 m0, s35
	s_nop 0
	global_load_lds_dwordx4 v[186:187], off
	s_waitcnt vmcnt(8)
	s_waitcnt lgkmcnt(0)
	s_barrier
	s_setprio 1
	s_waitcnt lgkmcnt(0)
	v_mfma_f32_16x16x32_bf16 v[60:63], v[142:145], v[174:177], v[60:63]
	v_mfma_f32_16x16x32_bf16 v[56:59], v[150:153], v[174:177], v[56:59]
	v_mfma_f32_16x16x32_bf16 v[44:47], v[142:145], v[182:185], v[44:47]
	v_mfma_f32_16x16x32_bf16 v[40:43], v[150:153], v[182:185], v[40:43]
	v_mfma_f32_16x16x32_bf16 v[28:31], v[142:145], v[200:203], v[28:31]
	v_mfma_f32_16x16x32_bf16 v[24:27], v[150:153], v[200:203], v[24:27]
	v_mfma_f32_16x16x32_bf16 v[12:15], v[142:145], v[208:211], v[12:15]
	v_mfma_f32_16x16x32_bf16 v[8:11], v[150:153], v[208:211], v[8:11]
	v_mfma_f32_16x16x32_bf16 v[60:63], v[146:149], v[178:181], v[60:63]
	v_mfma_f32_16x16x32_bf16 v[56:59], v[154:157], v[178:181], v[56:59]
	v_mfma_f32_16x16x32_bf16 v[44:47], v[146:149], v[196:199], v[44:47]
	v_mfma_f32_16x16x32_bf16 v[40:43], v[154:157], v[196:199], v[40:43]
	v_mfma_f32_16x16x32_bf16 v[28:31], v[146:149], v[204:207], v[28:31]
	v_mfma_f32_16x16x32_bf16 v[24:27], v[154:157], v[204:207], v[24:27]
	v_mfma_f32_16x16x32_bf16 v[12:15], v[146:149], v[212:215], v[12:15]
	v_mfma_f32_16x16x32_bf16 v[8:11], v[154:157], v[212:215], v[8:11]
	s_setprio 0
	s_setprio 1
	v_mfma_f32_16x16x32_bf16 v[52:55], v[158:161], v[174:177], v[52:55]
	v_mfma_f32_16x16x32_bf16 v[48:51], v[166:169], v[174:177], v[48:51]
	v_mfma_f32_16x16x32_bf16 v[36:39], v[158:161], v[182:185], v[36:39]
	v_mfma_f32_16x16x32_bf16 v[32:35], v[166:169], v[182:185], v[32:35]
	v_mfma_f32_16x16x32_bf16 v[20:23], v[158:161], v[200:203], v[20:23]
	v_mfma_f32_16x16x32_bf16 v[16:19], v[166:169], v[200:203], v[16:19]
	v_mfma_f32_16x16x32_bf16 v[4:7], v[158:161], v[208:211], v[4:7]
	v_mfma_f32_16x16x32_bf16 v[0:3], v[166:169], v[208:211], v[0:3]
	v_mfma_f32_16x16x32_bf16 v[52:55], v[162:165], v[178:181], v[52:55]
	v_mfma_f32_16x16x32_bf16 v[48:51], v[170:173], v[178:181], v[48:51]
	v_mfma_f32_16x16x32_bf16 v[36:39], v[162:165], v[196:199], v[36:39]
	v_mfma_f32_16x16x32_bf16 v[32:35], v[170:173], v[196:199], v[32:35]
	v_mfma_f32_16x16x32_bf16 v[20:23], v[162:165], v[204:207], v[20:23]
	v_mfma_f32_16x16x32_bf16 v[16:19], v[170:173], v[204:207], v[16:19]
	v_mfma_f32_16x16x32_bf16 v[4:7], v[162:165], v[212:215], v[4:7]
	v_mfma_f32_16x16x32_bf16 v[0:3], v[170:173], v[212:215], v[0:3]
	s_setprio 0
	s_barrier
	s_add_i32 s47, s47, 2
	s_add_u32 s45, s45, 0x100
	s_addc_u32 s46, s46, 0
	s_cmpk_gt_u32 s47, 0x55
	s_mov_b64 s[18:19], s[20:21]
	s_cbranch_scc0 .LBB0_1886
	s_branch .Lpeel_p11_done
	.p2align 6

; #define PG8_BAR __builtin_amdgcn_s_barrier()
; template <class Epi, class Sched, bool DEFER>
; __device__ __forceinline__ void gemm_fast_core(LAS unsigned char* lds, const GemmP g, const Sched& S, const Epi& E, f32x4 (&acc)[2][2][4][2], Unit& cur) {
;     ...
;         if (wr == 0) PG8_BAR;
;         if constexpr (DEFER) {   }
;         else if constexpr (Epi::TILE) E.tile(acc, cur, wr, wc, fr, fq);
;         else {
;             const int row0 = cur.pm * BM + wr * 64 + fr, col0 = cur.pn * BM + wc * 32 + 4 * fq;
; #pragma unroll
;             for (int ai = 0; ai < 2; ++ai)
; #pragma unroll
;                 for (int m = 0; m < 4; ++m)
; #pragma unroll
;                     for (int bj = 0; bj < 2; ++bj)
; #pragma unroll
;                         for (int n = 0; n < 2; ++n) E.put(cur, row0 + ai * HALF + m * 16, col0 + bj * HALF + n * 16, acc[ai][bj][m][n]);
;         }
;         if (!has_next) break;
; #pragma unroll
;         for (int a = 0; a < 2; ++a)
; #pragma unroll
;             for (int b = 0; b < 2; ++b)
; #pragma unroll
;                 for (int m = 0; m < 4; ++m)
; #pragma unroll
;                     for (int n = 0; n < 2; ++n) acc[a][b][m][n] = (f32x4){0.f, 0.f, 0.f, 0.f};
;         cur = nxt; cA = nA; cB = nB; ++ui;
;         if (wr == 1) PG8_BAR;
.Lpeel_p11_done:
	s_and_b64 vcc, exec, s[12:13]
	s_cbranch_vccz .LBB0_1889
	s_barrier
	s_and_b64 vcc, exec, s[2:3]
	s_mov_b64 s[2:3], -1
	s_cbranch_vccnz .LBB0_1874
	s_branch .LBB0_1890
